# attention tile loop back-edge rotation: loop-carried scalar work and priority raise moved in front of the half-step barrier
# baseline (speedup 1.0000x reference)
; #define SBAR() __builtin_amdgcn_sched_barrier(0)
; #define QK_RD(d0, sl) do { if ((d0) < 8) { const int a_ = kbase ^ (((d0) & 7) << 5); KRD(f0[sl], a_, 0); KRD(f1[sl], a_, 32 * 256); } \
;                            else { const int a_ = rbase ^ (((d0) & 3) << 5); KRD(f0[sl], a_, 0); KRD(f1[sl], a_, 32 * 128); } } while (0)
; #define PV_RD(d0, L, H) do { constexpr int b_ = v_rd_off(d0, 0, 0); TRRD(L[0], b_); TRRD(H[0], b_ + 2048); TRRD(L[1], b_ + 4096); TRRD(H[1], b_ + 6144); TRRD(L[2], b_ + 8192); TRRD(H[2], b_ + 10240); TRRD(L[3], b_ + 12288); TRRD(H[3], b_ + 14336); } while (0)
; #define LGKM(n) asm volatile("s_waitcnt lgkmcnt(" #n ")" ::: "memory")
; __device__ __forceinline__ void mphase(bool has_pv, f32x16* o, int vb, bf16x8 pa0, bf16x8 pa1, bf16x8 pa2, bf16x8 pa3, f32x16& p0, f32x16& p1, int kbase, int rbase, const bf16x8* qr) {
;     ...
;     if (has_pv) {
;         s16x4 la[4], ha[4], lb[4], hb[4];
;         PV_RD(0, la, ha); PV_RD(1, lb, hb);
;         LGKM(8); SBAR(); PV_MM(0, la, ha); SBAR();
;         PV_RD(2, la, ha); LGKM(8); SBAR(); PV_MM(1, lb, hb); SBAR();
;         PV_RD(3, lb, hb); LGKM(8); SBAR(); PV_MM(2, la, ha); SBAR();
;         LGKM(0); SBAR(); PV_MM(3, lb, hb); SBAR();
;     }
;     QK_RD(0, 0); QK_RD(1, 1);
;     p0 = f32x16{}; p1 = f32x16{};
; #pragma unroll
;     for (int d0 = 0; d0 < 12; ++d0) {
;         if (d0 + 2 < 12) { QK_RD(d0 + 2, (d0 + 2) % 3); LGKM(4); }
.Lattn_pv_entry:
	ds_read_b64_tr_b16 v[84:85], v199 offset:0x0
	ds_read_b64_tr_b16 v[86:87], v199 offset:0x800
	ds_read_b64_tr_b16 v[88:89], v199 offset:0x1000
	ds_read_b64_tr_b16 v[90:91], v199 offset:0x1800
	ds_read_b64_tr_b16 v[92:93], v199 offset:0x2000
	ds_read_b64_tr_b16 v[94:95], v199 offset:0x2800
	ds_read_b64_tr_b16 v[96:97], v199 offset:0x3000
	ds_read_b64_tr_b16 v[98:99], v199 offset:0x3800
	s_waitcnt lgkmcnt(6)
	v_mfma_f32_32x32x16_bf16 v[52:67], v[68:71], v[84:87], v[52:67]
	ds_read_b64_tr_b16 v[200:201], v199 offset:0x200
	ds_read_b64_tr_b16 v[202:203], v199 offset:0xa00
	s_waitcnt lgkmcnt(6)
	v_mfma_f32_32x32x16_bf16 v[52:67], v[72:75], v[88:91], v[52:67]
	ds_read_b64_tr_b16 v[204:205], v199 offset:0x1200
	ds_read_b64_tr_b16 v[206:207], v199 offset:0x1a00
	s_waitcnt lgkmcnt(6)
	v_mfma_f32_32x32x16_bf16 v[52:67], v[76:79], v[92:95], v[52:67]
	ds_read_b64_tr_b16 v[208:209], v199 offset:0x2200
	ds_read_b64_tr_b16 v[210:211], v199 offset:0x2a00
	s_waitcnt lgkmcnt(6)
	v_mfma_f32_32x32x16_bf16 v[52:67], v[80:83], v[96:99], v[52:67]
	ds_read_b64_tr_b16 v[212:213], v199 offset:0x3200
	ds_read_b64_tr_b16 v[214:215], v199 offset:0x3a00
	ds_read_b64_tr_b16 v[84:85], v199 offset:0x400
	ds_read_b64_tr_b16 v[86:87], v199 offset:0xc00
	s_waitcnt lgkmcnt(8)
	v_mfma_f32_32x32x16_bf16 v[36:51], v[68:71], v[200:203], v[36:51]
	ds_read_b64_tr_b16 v[88:89], v199 offset:0x1400
	ds_read_b64_tr_b16 v[90:91], v199 offset:0x1c00
	s_waitcnt lgkmcnt(8)
	v_mfma_f32_32x32x16_bf16 v[36:51], v[72:75], v[204:207], v[36:51]
	ds_read_b64_tr_b16 v[92:93], v199 offset:0x2400
	ds_read_b64_tr_b16 v[94:95], v199 offset:0x2c00
	s_waitcnt lgkmcnt(8)
	v_mfma_f32_32x32x16_bf16 v[36:51], v[76:79], v[208:211], v[36:51]
	ds_read_b64_tr_b16 v[96:97], v199 offset:0x3400
	ds_read_b64_tr_b16 v[98:99], v199 offset:0x3c00
	s_waitcnt lgkmcnt(8)
	v_mfma_f32_32x32x16_bf16 v[36:51], v[80:83], v[212:215], v[36:51]
	ds_read_b64_tr_b16 v[200:201], v199 offset:0x600
	ds_read_b64_tr_b16 v[202:203], v199 offset:0xe00
	s_waitcnt lgkmcnt(8)
	v_mfma_f32_32x32x16_bf16 v[20:35], v[68:71], v[84:87], v[20:35]
	ds_read_b64_tr_b16 v[204:205], v199 offset:0x1600
	ds_read_b64_tr_b16 v[206:207], v199 offset:0x1e00
	s_waitcnt lgkmcnt(8)
	v_mfma_f32_32x32x16_bf16 v[20:35], v[72:75], v[88:91], v[20:35]
	ds_read_b64_tr_b16 v[208:209], v199 offset:0x2600
	ds_read_b64_tr_b16 v[210:211], v199 offset:0x2e00
	s_waitcnt lgkmcnt(8)
	v_mfma_f32_32x32x16_bf16 v[20:35], v[76:79], v[92:95], v[20:35]
	ds_read_b64_tr_b16 v[212:213], v199 offset:0x3600
	ds_read_b64_tr_b16 v[214:215], v199 offset:0x3e00
	s_waitcnt lgkmcnt(8)
	v_mfma_f32_32x32x16_bf16 v[20:35], v[80:83], v[96:99], v[20:35]
	s_waitcnt lgkmcnt(6)
	v_mfma_f32_32x32x16_bf16 v[4:19], v[68:71], v[200:203], v[4:19]
	ds_read_b128 v[68:71], v3 offset:0
	s_waitcnt lgkmcnt(5)
	v_mfma_f32_32x32x16_bf16 v[4:19], v[72:75], v[204:207], v[4:19]
	ds_read_b128 v[72:75], v3 offset:0x2000
	v_xor_b32_e32 v199, 32, v3
	ds_read_b128 v[200:203], v199 offset:0
	s_waitcnt lgkmcnt(5)
	v_mfma_f32_32x32x16_bf16 v[4:19], v[76:79], v[208:211], v[4:19]
	ds_read_b128 v[204:207], v199 offset:0x2000
	s_waitcnt lgkmcnt(4)
	v_mfma_f32_32x32x16_bf16 v[4:19], v[80:83], v[212:215], v[4:19]
	v_xor_b32_e32 v76, 64, v3
	ds_read_b128 v[208:211], v76 offset:0
	ds_read_b128 v[212:215], v76 offset:0x2000
	s_branch .Lattn_qk

; #define SBAR() __builtin_amdgcn_sched_barrier(0)
; #define SLOAD(t) do { const int so_ = (t) * (KVBLK * 256); \
;         st_k0 = BLD(srdK, gofk, so_); st_k1 = BLD(srdK, gofk, so_ + 8192); st_v0 = BLD(srdV, gofk, so_); st_v1 = BLD(srdV, gofk, so_ + 8192); st_r = BLD(srdR, gofr, (t) * (KVBLK * 128)); } while (0)
; #define SWRITE(ts, v3) do { const int kb_ = ((ts) & 1) * SHM_K, rb_ = ((ts) & 1) * SHM_R, vb_ = (v3) * SHM_V; \
;         *(LAS bf16x8*)(lds + kb_ + kws) = st_k0; *(LAS bf16x8*)(lds + kb_ + kws + 32 * 256) = st_k1; \
;         *(LAS bf16x8*)(lds + vb_ + vst0) = st_v0; *(LAS bf16x8*)(lds + vb_ + vst1) = st_v1; *(LAS bf16x8*)(lds + rb_ + rws) = st_r; } while (0)
; __device__ __forceinline__ void attn_block(const Ptrs& P, int b, int h, int qb, LAS char* lds) {
;     ...
;     for (int x = 0; x < NT; ++x) {
;         SBAR(); __builtin_amdgcn_s_setprio(1);
;         mphase(x > 0, o, vb0 + pv3 * SHM_V, pa0, pa1, pa2, pa3, p0, p1, kbase, rbase, qr); if (x > 0) pv3 = pv3 == 2 ? 0 : pv3 + 1;
;         __builtin_amdgcn_s_setprio(0);
;         kbase ^= SHM_K; rbase ^= SHM_R;
;         __syncthreads();
;     ...
;         if (ts < NT) SWRITE(ts, ts3);
;         if (ts + 1 < NT) SLOAD(ts + 1);
;         ++ts; ts3 = ts3 == 2 ? 0 : ts3 + 1;
;         __syncthreads();
;     }
.LBB0_627:
	s_add_i32 s22, s83, 1
	s_cmp_lg_u32 s83, 2
	s_cselect_b32 s39, s22, 0
	s_and_b64 s[22:23], exec, s[56:57]
	s_cselect_b32 s83, s83, s39
	s_add_i32 s22, s38, 1
	s_cmp_lg_u32 s38, 2
	s_cselect_b32 s38, s22, 0
	s_sub_i32 s81, s81, 64
	s_addk_i32 s78, 0x2000
	s_addk_i32 s79, 0x4000
	s_add_i32 s22, s80, s81
	s_add_i32 s82, s82, 64
	s_add_i32 s77, s77, 1
	v_add_f32_e32 v198, v198, v85
	s_cmp_eq_u32 s22, 0
	s_waitcnt lgkmcnt(0)
	s_cbranch_scc1 .Lattn_exitbar
	s_mov_b64 s[56:57], 0
	v_lshl_add_u32 v199, s83, 14, v182
	s_setprio 1
	s_barrier
	s_branch .Lattn_pv_entry
.Lattn_exitbar:
	s_barrier
	s_branch .LBB0_629
